# stack20: GEMM phase prologues issue the K-tile-1 LDS-DMA loads before waiting for K-tile 0 (on top of stack19)
# baseline (speedup 1.0000x reference)
; #define PG8_STAGE(bufoff, gbase, voff) do { _Pragma("unroll") for (int _i = 0; _i < 2; ++_i) \
;         __builtin_amdgcn_global_load_lds((const unsigned*)((const char*)(gbase) + (voff)[_i]), (PG8_LAS unsigned*)(lds + (bufoff) + ldsw + _i * 8192), 16, 0, 0); } while (0)
; #define PG8_WAIT_V(n) asm volatile("s_waitcnt vmcnt(" #n ")" ::: "memory")
; #define PG8_BAR __builtin_amdgcn_s_barrier()
; template <class Epi, class Sched, bool ALIGN_EPI = false, bool SP2 = false>
; __device__ __forceinline__ void gemm_phase(PG8_LAS unsigned char* lds, const Gemm g, const Sched& S, const Epi& E, const int wid_in) {
;     ...
;     if constexpr (SP2) {
;         PG8_STAGE(PG8_SB(0, 0), cB, voffB); PG8_STAGE(PG8_SB(0, 1), cB + hstep, voffB); PG8_STAGE(PG8_SA(0, 0), cA, voffA); PG8_STAGE(PG8_SA(0, 1), cA + hstep, voffA);
;         if (wr == 1) PG8_BAR;
;         PG8_WAIT_V(2); PG8_BAR;
;         PG8_STAGE(PG8_SB(1, 0), cB + kstep, voffB); PG8_STAGE(PG8_SA(1, 0), cA + kstep, voffA); PG8_STAGE(PG8_SB(1, 1), cB + hstep + kstep, voffB);
;         PG8_WAIT_V(6); PG8_BAR;
.LBB0_99:
	v_readlane_b32 s50, v240, 45
	v_readlane_b32 s51, v240, 46
	v_mov_b32_e32 v131, v1
	v_readlane_b32 s48, v240, 41
	v_lshl_add_u64 v[10:11], s[50:51], 0, v[0:1]
	v_lshl_add_u64 v[12:13], s[50:51], 0, v[130:131]
	v_mov_b32_e32 v135, v1
	v_readlane_b32 s49, v240, 42
	v_lshl_add_u64 v[10:11], v[10:11], 0, s[64:65]
	s_add_i32 m0, s4, 0x18000
	v_lshl_add_u64 v[14:15], s[48:49], 0, v[134:135]
	v_mov_b32_e32 v133, v1
	global_load_lds_dwordx4 v[10:11], off
	v_lshl_add_u64 v[10:11], v[12:13], 0, s[64:65]
	s_add_i32 m0, s4, 0x1a000
	s_add_i32 s36, s4, 0x8000
	v_lshl_add_u64 v[16:17], s[48:49], 0, v[132:133]
	global_load_lds_dwordx4 v[10:11], off
	v_lshl_add_u64 v[10:11], v[14:15], 0, s[64:65]
	s_mov_b32 m0, s36
	s_add_i32 s37, s4, 0xa000
	v_readlane_b32 s8, v240, 47
	global_load_lds_dwordx4 v[10:11], off
	v_lshl_add_u64 v[10:11], v[16:17], 0, s[64:65]
	s_mov_b32 m0, s37
	v_readlane_b32 s9, v240, 48
	global_load_lds_dwordx4 v[10:11], off
	s_nop 0
	v_lshl_add_u64 v[10:11], s[8:9], 0, v[0:1]
	s_add_i32 m0, s4, 0x1c000
	v_and_b32_e32 v9, 15, v3
	global_load_lds_dwordx4 v[10:11], off
	v_lshl_add_u64 v[10:11], s[8:9], 0, v[130:131]
	s_add_i32 m0, s4, 0x1e000
	s_movk_i32 s2, 0x3c0
	global_load_lds_dwordx4 v[10:11], off
	s_waitcnt vmcnt(8)
	s_barrier
	v_or_b32_e32 v10, s67, v9
	v_and_b32_e32 v11, 48, v3
	v_lshlrev_b32_e32 v12, 6, v10
	v_lshlrev_b32_e32 v10, 2, v10
	v_and_or_b32 v12, v12, s2, v11
	v_and_b32_e32 v10, 32, v10
	v_readlane_b32 s2, v243, 58
	v_lshlrev_b32_e32 v3, 2, v3
	v_lshl_or_b32 v9, v9, 6, v11
	v_bitop3_b32 v10, v12, s2, v10 bitop3:0xde
	v_and_b32_e32 v3, 32, v3
	v_readlane_b32 s2, v243, 59
	s_waitcnt vmcnt(6)
	v_readlane_b32 s8, v240, 37
	v_mov_b32_e32 v137, v1
	v_bitop3_b32 v144, v9, s2, v3 bitop3:0xde
	v_lshlrev_b32_e32 v3, 14, v6
	v_and_b32_e32 v3, 0xffff8000, v3
	v_lshl_add_u32 v3, v7, 11, v3
	v_and_b32_e32 v6, 1, v6
	v_lshl_or_b32 v3, v6, 6, v3
	v_lshl_add_u32 v136, v8, 1, v3
	v_lshlrev_b32_e32 v3, 14, v2
	v_and_b32_e32 v3, 0xffff8000, v3
	v_lshl_add_u32 v3, v4, 11, v3
	v_and_b32_e32 v2, 1, v2
	v_lshl_or_b32 v2, v2, 6, v3
	v_lshl_add_u32 v138, v5, 1, v2
	v_mov_b32_e32 v139, v1
	s_mov_b32 s54, 0
	v_add_u32_e32 v145, 0, v10
	v_readlane_b32 s56, v241, 57
	s_mov_b32 s55, s8
	s_barrier
	v_readlane_b32 s9, v240, 38
	s_branch .LBB0_102

; #define PG8_STAGE(bufoff, gbase, voff) do { _Pragma("unroll") for (int _i = 0; _i < 2; ++_i) \
;         __builtin_amdgcn_global_load_lds((const unsigned*)((const char*)(gbase) + (voff)[_i]), (PG8_LAS unsigned*)(lds + (bufoff) + ldsw + _i * 8192), 16, 0, 0); } while (0)
; #define PG8_WAIT_V(n) asm volatile("s_waitcnt vmcnt(" #n ")" ::: "memory")
; #define PG8_BAR __builtin_amdgcn_s_barrier()
; template <class Epi, class Sched, bool ALIGN_EPI = false, bool SP2 = false>
; __device__ __forceinline__ void gemm_phase(PG8_LAS unsigned char* lds, const Gemm g, const Sched& S, const Epi& E, const int wid_in) {
;     ...
;     if constexpr (SP2) {
;         PG8_STAGE(PG8_SB(0, 0), cB, voffB); PG8_STAGE(PG8_SB(0, 1), cB + hstep, voffB); PG8_STAGE(PG8_SA(0, 0), cA, voffA); PG8_STAGE(PG8_SA(0, 1), cA + hstep, voffA);
;         if (wr == 1) PG8_BAR;
;         PG8_WAIT_V(2); PG8_BAR;
;         PG8_STAGE(PG8_SB(1, 0), cB + kstep, voffB); PG8_STAGE(PG8_SA(1, 0), cA + kstep, voffA); PG8_STAGE(PG8_SB(1, 1), cB + hstep + kstep, voffB);
;         PG8_WAIT_V(6); PG8_BAR;
.LBB0_258:
	v_readlane_b32 s40, v240, 6
	v_mov_b32_e32 v173, v1
	v_readlane_b32 s41, v240, 7
	v_mov_b32_e32 v171, v1
	v_readlane_b32 s50, v240, 2
	v_lshl_add_u64 v[2:3], s[40:41], 0, v[172:173]
	v_lshl_add_u64 v[4:5], s[40:41], 0, v[170:171]
	v_readlane_b32 s51, v240, 3
	v_lshl_add_u64 v[2:3], v[2:3], 0, s[64:65]
	s_add_i32 m0, s9, 0x18000
	v_lshl_add_u64 v[6:7], s[50:51], 0, v[172:173]
	global_load_lds_dwordx4 v[2:3], off
	v_lshl_add_u64 v[2:3], v[4:5], 0, s[64:65]
	s_add_i32 m0, s9, 0x1a000
	s_add_i32 s13, s9, 0x8000
	v_lshl_add_u64 v[8:9], s[50:51], 0, v[170:171]
	global_load_lds_dwordx4 v[2:3], off
	v_lshl_add_u64 v[2:3], v[6:7], 0, s[64:65]
	s_mov_b32 m0, s13
	s_add_i32 s12, s9, 0xa000
	v_readlane_b32 s4, v240, 8
	global_load_lds_dwordx4 v[2:3], off
	v_lshl_add_u64 v[2:3], v[8:9], 0, s[64:65]
	s_mov_b32 m0, s12
	v_readlane_b32 s5, v240, 9
	global_load_lds_dwordx4 v[2:3], off
	s_nop 0
	v_lshl_add_u64 v[2:3], s[4:5], 0, v[172:173]
	s_add_i32 m0, s9, 0x1c000
	v_and_b32_e32 v10, 15, v0
	global_load_lds_dwordx4 v[2:3], off
	v_lshl_add_u64 v[2:3], s[4:5], 0, v[170:171]
	s_add_i32 m0, s9, 0x1e000
	v_or_b32_e32 v11, s67, v10
	global_load_lds_dwordx4 v[2:3], off
	s_waitcnt vmcnt(8)
	s_barrier
	v_and_b32_e32 v12, 48, v0
	v_lshlrev_b32_e32 v13, 6, v11
	s_movk_i32 s2, 0x3c0
	v_lshlrev_b32_e32 v11, 2, v11
	v_and_or_b32 v13, v13, s2, v12
	v_and_b32_e32 v11, 32, v11
	v_readlane_b32 s2, v243, 58
	v_lshlrev_b32_e32 v0, 2, v0
	s_waitcnt vmcnt(6)
	v_readlane_b32 s4, v241, 60
	v_bitop3_b32 v11, v13, s2, v11 bitop3:0xde
	v_lshl_or_b32 v10, v10, 6, v12
	v_and_b32_e32 v0, 32, v0
	v_readlane_b32 s2, v243, 59
	v_readlane_b32 s5, v241, 61
	v_readlane_b32 s22, v241, 58
	v_bitop3_b32 v196, v10, s2, v0 bitop3:0xde
	s_mov_b32 s74, 0
	v_add_u32_e32 v197, 0, v11
	s_mov_b32 s5, s4
	s_mov_b32 s4, s22
	s_barrier
	v_readlane_b32 s23, v241, 59
	s_branch .LBB0_261

; #define PG8_STAGE(bufoff, gbase, voff) do { _Pragma("unroll") for (int _i = 0; _i < 2; ++_i) \
;         __builtin_amdgcn_global_load_lds((const unsigned*)((const char*)(gbase) + (voff)[_i]), (PG8_LAS unsigned*)(lds + (bufoff) + ldsw + _i * 8192), 16, 0, 0); } while (0)
; #define PG8_WAIT_V(n) asm volatile("s_waitcnt vmcnt(" #n ")" ::: "memory")
; #define PG8_BAR __builtin_amdgcn_s_barrier()
; template <class Epi, class Sched, bool ALIGN_EPI = false, bool SP2 = false>
; __device__ __forceinline__ void gemm_phase(PG8_LAS unsigned char* lds, const Gemm g, const Sched& S, const Epi& E, const int wid_in) {
;     ...
;     if constexpr (SP2) {
;         PG8_STAGE(PG8_SB(0, 0), cB, voffB); PG8_STAGE(PG8_SB(0, 1), cB + hstep, voffB); PG8_STAGE(PG8_SA(0, 0), cA, voffA); PG8_STAGE(PG8_SA(0, 1), cA + hstep, voffA);
;         if (wr == 1) PG8_BAR;
;         PG8_WAIT_V(2); PG8_BAR;
;         PG8_STAGE(PG8_SB(1, 0), cB + kstep, voffB); PG8_STAGE(PG8_SA(1, 0), cA + kstep, voffA); PG8_STAGE(PG8_SB(1, 1), cB + hstep + kstep, voffB);
;         PG8_WAIT_V(6); PG8_BAR;
.LBB0_527:
	v_and_b32_e32 v9, 15, v8
	v_or_b32_e32 v18, s67, v9
	v_readlane_b32 s50, v240, 18
	v_and_b32_e32 v19, 48, v8
	v_lshlrev_b32_e32 v20, 6, v18
	s_movk_i32 s2, 0x3c0
	v_lshlrev_b32_e32 v18, 2, v18
	v_readlane_b32 s51, v240, 19
	v_and_or_b32 v20, v20, s2, v19
	v_and_b32_e32 v18, 32, v18
	v_readlane_b32 s2, v243, 58
	v_lshlrev_b32_e32 v8, 2, v8
	v_lshl_add_u64 v[10:11], s[50:51], 0, v[0:1]
	v_mov_b32_e32 v131, v1
	v_readlane_b32 s48, v240, 14
	v_bitop3_b32 v18, v20, s2, v18 bitop3:0xde
	v_lshl_or_b32 v9, v9, 6, v19
	v_and_b32_e32 v8, 32, v8
	v_readlane_b32 s2, v241, 32
	v_lshl_add_u64 v[12:13], s[50:51], 0, v[130:131]
	v_mov_b32_e32 v135, v1
	v_readlane_b32 s49, v240, 15
	v_bitop3_b32 v142, v9, s2, v8 bitop3:0xde
	v_lshl_add_u64 v[8:9], v[10:11], 0, s[64:65]
	s_add_i32 m0, s4, 0x18000
	v_lshl_add_u64 v[14:15], s[48:49], 0, v[134:135]
	v_mov_b32_e32 v133, v1
	global_load_lds_dwordx4 v[8:9], off
	v_lshl_add_u64 v[8:9], v[12:13], 0, s[64:65]
	s_add_i32 m0, s4, 0x1a000
	s_add_i32 s36, s4, 0x8000
	v_lshl_add_u64 v[16:17], s[48:49], 0, v[132:133]
	global_load_lds_dwordx4 v[8:9], off
	v_lshl_add_u64 v[8:9], v[14:15], 0, s[64:65]
	s_mov_b32 m0, s36
	s_add_i32 s37, s4, 0xa000
	v_readlane_b32 s8, v240, 20
	global_load_lds_dwordx4 v[8:9], off
	v_lshl_add_u64 v[8:9], v[16:17], 0, s[64:65]
	s_mov_b32 m0, s37
	v_readlane_b32 s9, v240, 21
	global_load_lds_dwordx4 v[8:9], off
	s_nop 0
	v_lshl_add_u64 v[8:9], s[8:9], 0, v[0:1]
	s_add_i32 m0, s4, 0x1c000
	v_mov_b32_e32 v137, v1
	global_load_lds_dwordx4 v[8:9], off
	v_lshl_add_u64 v[8:9], s[8:9], 0, v[130:131]
	s_add_i32 m0, s4, 0x1e000
	v_readlane_b32 s8, v240, 25
	global_load_lds_dwordx4 v[8:9], off
	s_waitcnt vmcnt(8)
	s_barrier
	v_lshlrev_b32_e32 v8, 14, v5
	v_and_b32_e32 v8, 0xffff8000, v8
	v_lshl_add_u32 v6, v6, 11, v8
	v_and_b32_e32 v5, 1, v5
	v_lshl_or_b32 v5, v5, 6, v6
	v_lshl_add_u32 v136, v7, 1, v5
	v_lshlrev_b32_e32 v5, 14, v2
	v_and_b32_e32 v5, 0xffff8000, v5
	s_waitcnt vmcnt(6)
	v_lshl_add_u32 v3, v3, 11, v5
	v_and_b32_e32 v2, 1, v2
	v_lshl_or_b32 v2, v2, 6, v3
	v_lshl_add_u32 v138, v4, 1, v2
	v_mov_b32_e32 v139, v1
	s_mov_b32 s54, 0
	v_add_u32_e32 v143, 0, v18
	v_readlane_b32 s55, v240, 22
	s_mov_b32 s56, s8
	s_barrier
	v_readlane_b32 s9, v240, 26
	s_waitcnt vmcnt(0)
	s_branch .LBB0_530

; #define PG8_STAGE(bufoff, gbase, voff) do { _Pragma("unroll") for (int _i = 0; _i < 2; ++_i) \
;         __builtin_amdgcn_global_load_lds((const unsigned*)((const char*)(gbase) + (voff)[_i]), (PG8_LAS unsigned*)(lds + (bufoff) + ldsw + _i * 8192), 16, 0, 0); } while (0)
; #define PG8_WAIT_V(n) asm volatile("s_waitcnt vmcnt(" #n ")" ::: "memory")
; #define PG8_BAR __builtin_amdgcn_s_barrier()
; template <class Epi, class Sched, bool ALIGN_EPI = false, bool SP2 = false>
; __device__ __forceinline__ void gemm_phase(PG8_LAS unsigned char* lds, const Gemm g, const Sched& S, const Epi& E, const int wid_in) {
;     ...
;     if constexpr (SP2) {
;         PG8_STAGE(PG8_SB(0, 0), cB, voffB); PG8_STAGE(PG8_SB(0, 1), cB + hstep, voffB); PG8_STAGE(PG8_SA(0, 0), cA, voffA); PG8_STAGE(PG8_SA(0, 1), cA + hstep, voffA);
;         if (wr == 1) PG8_BAR;
;         PG8_WAIT_V(2); PG8_BAR;
;         PG8_STAGE(PG8_SB(1, 0), cB + kstep, voffB); PG8_STAGE(PG8_SA(1, 0), cA + kstep, voffA); PG8_STAGE(PG8_SB(1, 1), cB + hstep + kstep, voffB);
;         PG8_WAIT_V(6); PG8_BAR;
.LBB0_699:
	v_readlane_b32 s44, v240, 61
	v_readlane_b32 s45, v240, 62
	v_mov_b32_e32 v195, v1
	v_readlane_b32 s42, v240, 57
	v_lshl_add_u64 v[2:3], s[44:45], 0, v[0:1]
	v_lshl_add_u64 v[4:5], s[44:45], 0, v[194:195]
	v_mov_b32_e32 v191, v1
	v_readlane_b32 s43, v240, 58
	v_lshl_add_u64 v[2:3], v[2:3], 0, s[64:65]
	s_add_i32 m0, s12, 0x18000
	v_lshl_add_u64 v[14:15], s[42:43], 0, v[190:191]
	v_mov_b32_e32 v193, v1
	global_load_lds_dwordx4 v[2:3], off
	v_lshl_add_u64 v[2:3], v[4:5], 0, s[64:65]
	s_add_i32 m0, s12, 0x1a000
	s_add_i32 s78, s12, 0x8000
	v_lshl_add_u64 v[16:17], s[42:43], 0, v[192:193]
	global_load_lds_dwordx4 v[2:3], off
	v_lshl_add_u64 v[2:3], v[14:15], 0, s[64:65]
	s_mov_b32 m0, s78
	s_add_i32 s79, s12, 0xa000
	v_readlane_b32 s8, v240, 63
	global_load_lds_dwordx4 v[2:3], off
	v_lshl_add_u64 v[2:3], v[16:17], 0, s[64:65]
	s_mov_b32 m0, s79
	v_readlane_b32 s9, v239, 0
	global_load_lds_dwordx4 v[2:3], off
	s_nop 0
	v_lshl_add_u64 v[2:3], s[8:9], 0, v[0:1]
	s_add_i32 m0, s12, 0x1c000
	v_and_b32_e32 v13, 15, v12
	global_load_lds_dwordx4 v[2:3], off
	v_lshl_add_u64 v[2:3], s[8:9], 0, v[194:195]
	s_add_i32 m0, s12, 0x1e000
	v_or_b32_e32 v18, s67, v13
	global_load_lds_dwordx4 v[2:3], off
	s_waitcnt vmcnt(8)
	s_barrier
	v_lshlrev_b32_e32 v2, 14, v6
	v_and_b32_e32 v2, 0xffff8000, v2
	v_lshl_add_u32 v2, v7, 11, v2
	v_and_b32_e32 v3, 1, v6
	v_lshl_or_b32 v2, v3, 6, v2
	v_lshl_add_u32 v196, v8, 1, v2
	v_lshlrev_b32_e32 v2, 14, v9
	v_and_b32_e32 v19, 48, v12
	v_lshlrev_b32_e32 v20, 6, v18
	s_movk_i32 s5, 0x3c0
	v_lshlrev_b32_e32 v18, 2, v18
	s_or_b32 s96, s2, s31
	v_readlane_b32 s2, v239, 11
	v_and_b32_e32 v2, 0xffff8000, v2
	v_and_or_b32 v20, v20, s5, v19
	v_and_b32_e32 v18, 32, v18
	v_readlane_b32 s5, v243, 58
	v_lshlrev_b32_e32 v12, 2, v12
	s_waitcnt vmcnt(6)
	s_or_b32 s2, s4, s2
	v_lshl_add_u32 v2, v10, 11, v2
	v_and_b32_e32 v3, 1, v9
	v_bitop3_b32 v18, v20, s5, v18 bitop3:0xde
	v_lshl_or_b32 v13, v13, 6, v19
	v_and_b32_e32 v12, 32, v12
	v_readlane_b32 s5, v243, 59
	s_lshl_b32 s2, s2, 7
	v_lshl_or_b32 v2, v3, 6, v2
	v_readlane_b32 s8, v240, 49
	v_bitop3_b32 v211, v13, s5, v12 bitop3:0xde
	s_or_b32 s97, s2, s31
	s_mov_b32 s4, 1
	v_mov_b32_e32 v197, v1
	v_lshl_add_u32 v198, v11, 1, v2
	v_mov_b32_e32 v199, v1
	v_add_u32_e32 v212, 0, v18
	v_readlane_b32 s51, v240, 52
	s_mov_b32 s50, s8
	s_mov_b32 s5, 0
	s_barrier
	v_readlane_b32 s9, v240, 50
	s_waitcnt vmcnt(0)
	s_branch .LBB0_702

; #define PG8_STAGE(bufoff, gbase, voff) do { _Pragma("unroll") for (int _i = 0; _i < 2; ++_i) \
;         __builtin_amdgcn_global_load_lds((const unsigned*)((const char*)(gbase) + (voff)[_i]), (PG8_LAS unsigned*)(lds + (bufoff) + ldsw + _i * 8192), 16, 0, 0); } while (0)
; #define PG8_WAIT_V(n) asm volatile("s_waitcnt vmcnt(" #n ")" ::: "memory")
; #define PG8_BAR __builtin_amdgcn_s_barrier()
; template <class Epi, class Sched, bool ALIGN_EPI = false, bool SP2 = false>
; __device__ __forceinline__ void gemm_phase(PG8_LAS unsigned char* lds, const Gemm g, const Sched& S, const Epi& E, const int wid_in) {
;     ...
;     if constexpr (SP2) {
;         PG8_STAGE(PG8_SB(0, 0), cB, voffB); PG8_STAGE(PG8_SB(0, 1), cB + hstep, voffB); PG8_STAGE(PG8_SA(0, 0), cA, voffA); PG8_STAGE(PG8_SA(0, 1), cA + hstep, voffA);
;         if (wr == 1) PG8_BAR;
;         PG8_WAIT_V(2); PG8_BAR;
;         PG8_STAGE(PG8_SB(1, 0), cB + kstep, voffB); PG8_STAGE(PG8_SA(1, 0), cA + kstep, voffA); PG8_STAGE(PG8_SB(1, 1), cB + hstep + kstep, voffB);
;         PG8_WAIT_V(6); PG8_BAR;
.LBB0_809:
	v_and_b32_e32 v11, 15, v10
	v_or_b32_e32 v20, s67, v11
	v_readlane_b32 s46, v240, 33
	v_and_b32_e32 v21, 48, v10
	v_lshlrev_b32_e32 v22, 6, v20
	s_movk_i32 s2, 0x3c0
	v_lshlrev_b32_e32 v20, 2, v20
	v_readlane_b32 s47, v240, 34
	v_and_or_b32 v22, v22, s2, v21
	v_and_b32_e32 v20, 32, v20
	v_readlane_b32 s2, v243, 58
	v_lshlrev_b32_e32 v10, 2, v10
	v_lshl_add_u64 v[12:13], s[46:47], 0, v[0:1]
	v_mov_b32_e32 v131, v1
	v_readlane_b32 s44, v240, 29
	v_bitop3_b32 v20, v22, s2, v20 bitop3:0xde
	v_lshl_or_b32 v11, v11, 6, v21
	v_and_b32_e32 v10, 32, v10
	v_readlane_b32 s2, v241, 32
	v_lshl_add_u64 v[14:15], s[46:47], 0, v[130:131]
	v_mov_b32_e32 v135, v1
	v_readlane_b32 s45, v240, 30
	v_bitop3_b32 v142, v11, s2, v10 bitop3:0xde
	v_lshl_add_u64 v[10:11], v[12:13], 0, s[64:65]
	s_add_i32 m0, s4, 0x18000
	v_lshl_add_u64 v[16:17], s[44:45], 0, v[134:135]
	v_mov_b32_e32 v133, v1
	global_load_lds_dwordx4 v[10:11], off
	v_lshl_add_u64 v[10:11], v[14:15], 0, s[64:65]
	s_add_i32 m0, s4, 0x1a000
	s_add_i32 s36, s4, 0x8000
	v_lshl_add_u64 v[18:19], s[44:45], 0, v[132:133]
	global_load_lds_dwordx4 v[10:11], off
	v_lshl_add_u64 v[10:11], v[16:17], 0, s[64:65]
	s_mov_b32 m0, s36
	s_add_i32 s37, s4, 0xa000
	v_readlane_b32 s8, v240, 35
	global_load_lds_dwordx4 v[10:11], off
	v_lshl_add_u64 v[10:11], v[18:19], 0, s[64:65]
	s_mov_b32 m0, s37
	v_readlane_b32 s9, v240, 36
	global_load_lds_dwordx4 v[10:11], off
	s_nop 0
	v_lshl_add_u64 v[10:11], s[8:9], 0, v[0:1]
	s_add_i32 m0, s4, 0x1c000
	s_movk_i32 s2, 0xb00
	global_load_lds_dwordx4 v[10:11], off
	v_lshl_add_u64 v[10:11], s[8:9], 0, v[130:131]
	s_add_i32 m0, s4, 0x1e000
	s_mov_b32 s8, 0xb000
	global_load_lds_dwordx4 v[10:11], off
	s_waitcnt vmcnt(8)
	s_barrier
	v_lshrrev_b32_e32 v10, 1, v6
	v_mul_lo_u32 v6, v7, s2
	v_mad_u64_u32 v[6:7], s[22:23], v10, s8, v[6:7]
	v_or_b32_e32 v6, v6, v8
	v_add_lshl_u32 v6, v6, v9, 1
	v_mov_b32_e32 v7, v1
	s_mov_b64 s[26:27], 0xb0080
	v_lshl_add_u64 v[136:137], v[6:7], 0, s[26:27]
	v_lshrrev_b32_e32 v6, 1, v2
	v_mul_lo_u32 v2, v3, s2
	v_mad_u64_u32 v[2:3], s[22:23], v6, s8, v[2:3]
	s_waitcnt vmcnt(6)
	v_or_b32_e32 v2, v2, v4
	v_add_lshl_u32 v2, v2, v5, 1
	v_mov_b32_e32 v3, v1
	v_readlane_b32 s8, v240, 25
	v_lshl_add_u64 v[138:139], v[2:3], 0, s[26:27]
	s_mov_b32 s52, 0
	v_add_u32_e32 v143, 0, v20
	v_readlane_b32 s55, v240, 22
	s_mov_b32 s56, s8
	s_barrier
	v_readlane_b32 s9, v240, 26
	s_branch .LBB0_812
